# phase 0: a wave converts either one w_in_ab block or x rows (two rows per trip); final norm two rows per trip
# baseline (speedup 1.0000x reference)
; DI void phase0(CP& p, LAS unsigned char* lds, int wid) {
;     ...
;     constexpr int NCONV = 5520, NXROW = 8192;
;     const int gw = blockIdx.x * 8 + wid, nw = gridDim.x * 8;
;     for (int it0 = gw; it0 < NCONV + NXROW; it0 += nw) {
;         const int it = it0 < NCONV ? NCONV - 1 - it0 : it0;
.Lconv_entry:
	s_lshl_b32 s2, s6, 3
	v_mbcnt_hi_u32_b32 v5, -1, v254
	s_add_i32 s89, s33, s2
	s_cmp_lg_u32 s98, 0
	s_cbranch_scc1 .Lconv_ext
	s_movk_i32 s101, 0x358f
	s_lshl_b32 s100, s7, 3
	s_cmpk_lg_i32 s7, 0x100
	s_cbranch_scc1 .Lconv_go
	s_mul_i32 s89, s33, s7
	s_add_i32 s89, s89, s6
	s_cmpk_lt_u32 s89, 384
	s_cbranch_scc1 .Lconv_heavy
	s_addk_i32 s89, 5136
	s_movk_i32 s100, 1664
	s_branch .Lconv_go
.Lconv_heavy:
	s_addk_i32 s89, 5136
	s_movk_i32 s100, 0x4000
	s_branch .Lconv_go

; #define LAS __attribute__((address_space(3)))
; DI int lane_id() { int l = __builtin_amdgcn_mbcnt_hi(-1, __builtin_amdgcn_mbcnt_lo(-1, 0)); asm volatile("" : "+v"(l)); return l; }
; DI void conv_item(int lane, LAS unsigned char* wl, const float* src, const float* src2, const float* gain, bf16_t* dst, int ld, int K, int mode, int coff, int item) {
;     const int nkc = K >> 8; const int pt = item / nkc, kc = item - pt * nkc;
;     const bool gu = (mode == CM_GU);
;     ...
;     const int pp = CV_POS(lane), k0 = kc * 256; const float* s = src; long col = pp + coff; bool zero = false;
;     if (mode == CM_UZ) col = pp < 1024 ? pp : pp + 1024;
;     else if (mode == CM_GU) { const int n = (lane >> 4) & 1, r = lane & 15; col = (pt >> 2) * 128 + (pt & 3) * 32 + 8 * (r >> 2) + 4 * (lane >> 5) + (r & 3); s = n ? src2 : src; }
;     else if (mode == CM_P32) { const int rho = pp & 31; col = (pp & ~31) + 8 * ((rho & 15) >> 2) + 4 * (rho >> 4) + (rho & 3); }
;     else if (mode == CM_POOL) col = (long)(pp >> 8) * 65536 + (pp & 255);
;     else if (mode == CM_INC) { if (pp >= 1088) { zero = true; col = 0; } else if (pp >= 1024) { const int q = pp - 1024, w = q >> 5, t = q & 31; col = 1024 + 32 * ((t >> 2) & 1) + 16 * w + 4 * (t >> 3) + (t & 3); } }
;     else if (mode == CM_UQ) { const int g64 = pp >> 6; if ((g64 % 3) == 2) { const int q = pp & 63, w = q >> 5, t = q & 31; col = g64 * 64 + 32 * ((t >> 2) & 1) + 16 * w + 4 * (t >> 3) + (t & 3); } }
;     else if (mode == CM_UKVK) col = (pp >> 7) * 256 + (pp & 127);
;     else if (mode == CM_UKVV) col = (pp >> 7) * 256 + 128 + (pp & 127);
;     const float* sp = s + (size_t)k0 * ld + col; bf16_t* dp = dst + (size_t)CV_POS(lane >> 3) * K + k0 + (lane & 7) * 8;
;     const size_t rstep = (size_t)8 * K, hstep = (size_t)(gu ? 128 : 32) * K;
; DI void phase0(CP& p, LAS unsigned char* lds, int wid) {
;     const int lane = lane_id(), tid = wid * 64 + lane;
;     constexpr int NCONV = 5520, NXROW = 8192;
;     const int gw = blockIdx.x * 8 + wid, nw = gridDim.x * 8;
;     for (int it0 = gw; it0 < NCONV + NXROW; it0 += nw) {
;         const int it = it0 < NCONV ? NCONV - 1 - it0 : it0;
;         if (it < NCONV) {
;             const float* src; const float* src2 = nullptr; const float* gain = nullptr; bf16_t* dst; int ld, K, mode = CM_ID, coff = 0, t0;
.Lconv_go:
	s_mov_b64 s[38:39], s[0:1]
	s_mov_b32 s41, 0
	v_mov_b32_e32 v0, v5
	s_cmp_gt_i32 s89, s101
	s_cbranch_scc1 .LBB0_225
	s_load_dwordx4 s[24:27], s[38:39], 0x0
	s_load_dwordx2 s[4:5], s[38:39], 0x10
	s_load_dwordx2 s[44:45], s[38:39], 0xa8
	s_load_dwordx4 s[28:31], s[38:39], 0x90
	s_lshl_b32 s90, s7, 3
	s_mov_b32 s90, s100
	v_ashrrev_i32_e32 v1, 31, v0
	s_waitcnt lgkmcnt(0)
	v_mov_b32_e32 v2, s24
	s_add_u32 s91, s44, 0xcd00000
	s_addc_u32 s92, s45, 0
	s_add_u32 s8, s28, 0x2c00000
	v_writelane_b32 v255, s8, 0
	s_addc_u32 s8, s29, 0
	v_writelane_b32 v255, s8, 1
	s_add_u32 s4, s4, 0x2000
	v_writelane_b32 v255, s4, 2
	s_addc_u32 s4, s5, 0
	s_add_u32 s24, s44, 0x6300000
	v_mov_b32_e32 v3, s25
	s_addc_u32 s25, s45, 0
	s_add_u32 s46, s44, 0x6100000
	s_addc_u32 s47, s45, 0
	s_add_u32 s48, s44, 0x5f00000
	s_addc_u32 s49, s45, 0
	v_lshl_add_u64 v[2:3], v[0:1], 4, v[2:3]
	v_and_b32_e32 v1, 64, v5
	s_add_u32 s50, s44, 0x5c00000
	v_lshlrev_b32_e32 v4, 1, v0
	v_and_b32_e32 v9, 3, v0
	v_add_u32_e32 v8, 64, v1
	s_addc_u32 s51, s45, 0
	v_and_or_b32 v4, v4, 24, v9
	v_xor_b32_e32 v9, 1, v5
	s_add_u32 s52, s26, 0x2000
	v_cmp_lt_i32_e32 vcc, v9, v8
	s_addc_u32 s53, s27, 0
	s_add_u32 s54, s44, 0x5700000
	v_cndmask_b32_e32 v9, v5, v9, vcc
	v_lshlrev_b32_e32 v224, 2, v9
	v_xor_b32_e32 v9, 2, v5
	s_addc_u32 s55, s45, 0
	v_cmp_lt_i32_e32 vcc, v9, v8
	s_add_u32 s58, s44, 0x5600000
	s_addc_u32 s59, s45, 0
	v_cndmask_b32_e32 v9, v5, v9, vcc
	v_lshlrev_b32_e32 v225, 2, v9
	v_xor_b32_e32 v9, 4, v5
	s_add_u32 s60, s44, 0x4000000
	v_cmp_lt_i32_e32 vcc, v9, v8
	s_addc_u32 s61, s45, 0
	s_add_u32 s62, s44, 0x1400000
	v_cndmask_b32_e32 v9, v5, v9, vcc
	v_lshlrev_b32_e32 v226, 2, v9
	v_xor_b32_e32 v9, 8, v5
	s_addc_u32 s63, s45, 0
	v_cmp_lt_i32_e32 vcc, v9, v8
	s_add_u32 s64, s44, 0xc00000
	v_ashrrev_i32_e32 v220, 3, v0
	v_cndmask_b32_e32 v9, v5, v9, vcc
	s_addc_u32 s65, s45, 0
	v_and_b32_e32 v7, -4, v220
	v_lshlrev_b32_e32 v227, 2, v9
	v_xor_b32_e32 v9, 16, v5
	v_writelane_b32 v255, s4, 3
	s_add_u32 s66, s44, 0x800000
	s_mul_i32 s4, s33, 0x2400
	v_add_u32_e32 v221, v4, v7
	v_and_b32_e32 v4, 16, v0
	v_cmp_lt_i32_e32 vcc, v9, v8
	s_addc_u32 s67, s45, 0
	s_add_i32 s40, s4, 0
	v_lshlrev_b32_e32 v6, 2, v0
	s_movk_i32 s8, 0xff80
	v_cmp_eq_u32_e64 s[4:5], 0, v4
	v_bfe_u32 v4, v0, 3, 5
	v_ashrrev_i32_e32 v7, 1, v0
	v_cndmask_b32_e32 v9, v5, v9, vcc
	v_and_or_b32 v223, v7, s8, v4
	s_movk_i32 s8, 0x90
	v_ashrrev_i32_e32 v7, 31, v6
	v_lshlrev_b32_e32 v228, 2, v9
	v_xor_b32_e32 v9, 32, v5
	v_and_b32_e32 v1, 0xffffff80, v6
	v_mul_lo_u32 v10, v0, s8
	v_cmp_lt_i32_e32 vcc, v9, v8
	v_mul_lo_u32 v8, v220, s8
	v_lshl_add_u64 v[6:7], v[6:7], 1, s[44:45]
	s_mov_b64 s[8:9], 0xad00000
	s_load_dwordx2 s[56:57], s[38:39], 0x20
	v_lshl_add_u64 v[6:7], v[6:7], 0, s[8:9]
	s_load_dwordx16 s[8:23], s[38:39], 0x50
	v_lshlrev_b32_e32 v4, 4, v0
	v_and_b32_e32 v4, 0x70, v4
	v_add_u32_e32 v11, s40, v4
	v_cndmask_b32_e32 v5, v5, v9, vcc
	v_mov_b32_e32 v9, 0
	v_cmp_eq_u32_e64 s[2:3], 0, v0
	v_and_or_b32 v1, v0, 31, v1
	v_lshlrev_b32_e32 v229, 2, v5
	v_mov_b32_e32 v5, v9
	s_movk_i32 s97, 0x400
	v_add_u32_e32 v230, s40, v10
	v_add_u32_e32 v231, v11, v8
	s_mov_b64 s[68:69], 0x80
	s_branch .LBB0_23

; DI u32x2 pk4(f32x4 v) { u32x2 r; r.x = pk2(v[0], v[1]); r.y = pk2(v[2], v[3]); return r; }
; DI void phase0(CP& p, LAS unsigned char* lds, int wid) {
;     ...
;             const int row = it - NCONV; const f32x4* xr = (const f32x4*)(p.x + (size_t)row * 2048); bf16_t* xb = WSB(OFF_XB) + (size_t)row * 2048;
;             float ss = 0.f;
; #pragma unroll
;             for (int i = 0; i < 8; ++i) { const f32x4 v = __builtin_nontemporal_load(xr + i * 64 + lane); ss += v[0] * v[0] + v[1] * v[1] + v[2] * v[2] + v[3] * v[3]; *(u32x2*)(xb + (i * 64 + lane) * 4) = pk4(v); }
; #pragma unroll
;             for (int o = 1; o < 64; o <<= 1) ss += __shfl_xor(ss, o);
;             if (lane == 0) SSQ(0)[row] = ss;
.LBB0_23:
	s_sub_i32 s40, 0x158f, s89
	s_cmpk_lt_i32 s89, 0x1590
	s_cselect_b32 s84, s40, s89
	s_cmpk_gt_i32 s84, 0x158f
	s_mov_b64 s[70:71], -1
	s_cbranch_scc0 .LBB0_27
	s_add_i32 s40, s84, 0xffffea70
	s_lshl_b64 s[42:43], s[40:41], 13
	s_add_u32 s42, s42, 0x1000
	s_addc_u32 s43, s43, 0
	v_lshl_add_u64 v[44:45], v[2:3], 0, s[42:43]
	s_waitcnt lgkmcnt(0)
	global_load_dwordx4 v[10:13], v[44:45], off offset:-4096 nt
	global_load_dwordx4 v[14:17], v[44:45], off offset:-3072 nt
	global_load_dwordx4 v[18:21], v[44:45], off offset:-2048 nt
	global_load_dwordx4 v[22:25], v[44:45], off offset:-1024 nt
	global_load_dwordx4 v[26:29], v[44:45], off offset:0 nt
	global_load_dwordx4 v[30:33], v[44:45], off offset:1024 nt
	global_load_dwordx4 v[34:37], v[44:45], off offset:2048 nt
	global_load_dwordx4 v[38:41], v[44:45], off offset:3072 nt
	s_add_i32 s76, s89, s90
	s_cmp_le_i32 s76, s101
	s_cselect_b32 s77, 1, 0
	s_cbranch_scc0 .Lxr_noB
	s_add_i32 s72, s40, s90
	s_mov_b32 s73, 0
	s_lshl_b64 s[74:75], s[72:73], 13
	s_add_u32 s74, s74, 0x1000
	s_addc_u32 s75, s75, 0
	v_lshl_add_u64 v[84:85], v[2:3], 0, s[74:75]
	global_load_dwordx4 v[52:55], v[84:85], off offset:-4096 nt
	global_load_dwordx4 v[56:59], v[84:85], off offset:-3072 nt
	global_load_dwordx4 v[60:63], v[84:85], off offset:-2048 nt
	global_load_dwordx4 v[64:67], v[84:85], off offset:-1024 nt
	global_load_dwordx4 v[68:71], v[84:85], off offset:0 nt
	global_load_dwordx4 v[72:75], v[84:85], off offset:1024 nt
	global_load_dwordx4 v[76:79], v[84:85], off offset:2048 nt
	global_load_dwordx4 v[80:83], v[84:85], off offset:3072 nt
	s_lshl_b64 s[74:75], s[72:73], 12
	v_lshl_add_u64 v[86:87], v[6:7], 0, s[74:75]
.Lxr_noB:
	s_lshl_b64 s[42:43], s[40:41], 12
	v_lshl_add_u64 v[42:43], v[6:7], 0, s[42:43]
	s_cmp_eq_u32 s77, 0
	s_cbranch_scc1 .Lxr_A1
	s_waitcnt vmcnt(15)
	v_cvt_pk_bf16_f32 v46, v10, v11
	v_cvt_pk_bf16_f32 v47, v12, v13
	global_store_dwordx2 v[42:43], v[46:47], off
	v_mul_f32_e32 v50, v11, v11
	v_fmac_f32_e32 v50, v10, v10
	v_fmac_f32_e32 v50, v12, v12
	v_fmac_f32_e32 v50, v13, v13
	v_mov_b32_e32 v8, v50
	s_waitcnt vmcnt(15)
	v_cvt_pk_bf16_f32 v48, v14, v15
	v_cvt_pk_bf16_f32 v49, v16, v17
	global_store_dwordx2 v[42:43], v[48:49], off offset:512
	v_mul_f32_e32 v50, v15, v15
	v_fmac_f32_e32 v50, v14, v14
	v_fmac_f32_e32 v50, v16, v16
	v_fmac_f32_e32 v50, v17, v17
	v_add_f32_e32 v8, v8, v50
	s_waitcnt vmcnt(15)
	v_cvt_pk_bf16_f32 v46, v18, v19
	v_cvt_pk_bf16_f32 v47, v20, v21
	global_store_dwordx2 v[42:43], v[46:47], off offset:1024
	v_mul_f32_e32 v50, v19, v19
	v_fmac_f32_e32 v50, v18, v18
	v_fmac_f32_e32 v50, v20, v20
	v_fmac_f32_e32 v50, v21, v21
	v_add_f32_e32 v8, v8, v50
	s_waitcnt vmcnt(15)
	v_cvt_pk_bf16_f32 v48, v22, v23
	v_cvt_pk_bf16_f32 v49, v24, v25
	global_store_dwordx2 v[42:43], v[48:49], off offset:1536
	v_mul_f32_e32 v50, v23, v23
	v_fmac_f32_e32 v50, v22, v22
	v_fmac_f32_e32 v50, v24, v24
	v_fmac_f32_e32 v50, v25, v25
	v_add_f32_e32 v8, v8, v50
	s_waitcnt vmcnt(15)
	v_cvt_pk_bf16_f32 v46, v26, v27
	v_cvt_pk_bf16_f32 v47, v28, v29
	global_store_dwordx2 v[42:43], v[46:47], off offset:2048
	v_mul_f32_e32 v50, v27, v27
	v_fmac_f32_e32 v50, v26, v26
	v_fmac_f32_e32 v50, v28, v28
	v_fmac_f32_e32 v50, v29, v29
	v_add_f32_e32 v8, v8, v50
	s_waitcnt vmcnt(15)
	v_cvt_pk_bf16_f32 v48, v30, v31
	v_cvt_pk_bf16_f32 v49, v32, v33
	global_store_dwordx2 v[42:43], v[48:49], off offset:2560
	v_mul_f32_e32 v50, v31, v31
	v_fmac_f32_e32 v50, v30, v30
	v_fmac_f32_e32 v50, v32, v32
	v_fmac_f32_e32 v50, v33, v33
	v_add_f32_e32 v8, v8, v50
	s_waitcnt vmcnt(15)
	v_cvt_pk_bf16_f32 v46, v34, v35
	v_cvt_pk_bf16_f32 v47, v36, v37
	global_store_dwordx2 v[42:43], v[46:47], off offset:3072
	v_mul_f32_e32 v50, v35, v35
	v_fmac_f32_e32 v50, v34, v34
	v_fmac_f32_e32 v50, v36, v36
	v_fmac_f32_e32 v50, v37, v37
	v_add_f32_e32 v8, v8, v50
	s_waitcnt vmcnt(15)
	v_cvt_pk_bf16_f32 v48, v38, v39
	v_cvt_pk_bf16_f32 v49, v40, v41
	global_store_dwordx2 v[42:43], v[48:49], off offset:3584
	v_mul_f32_e32 v50, v39, v39
	v_fmac_f32_e32 v50, v38, v38
	v_fmac_f32_e32 v50, v40, v40
	v_fmac_f32_e32 v50, v41, v41
	v_add_f32_e32 v8, v8, v50
	s_waitcnt vmcnt(15)
	v_cvt_pk_bf16_f32 v46, v52, v53
	v_cvt_pk_bf16_f32 v47, v54, v55
	global_store_dwordx2 v[86:87], v[46:47], off
	v_mul_f32_e32 v50, v53, v53
	v_fmac_f32_e32 v50, v52, v52
	v_fmac_f32_e32 v50, v54, v54
	v_fmac_f32_e32 v50, v55, v55
	v_mov_b32_e32 v88, v50
	s_waitcnt vmcnt(15)
	v_cvt_pk_bf16_f32 v48, v56, v57
	v_cvt_pk_bf16_f32 v49, v58, v59
	global_store_dwordx2 v[86:87], v[48:49], off offset:512
	v_mul_f32_e32 v50, v57, v57
	v_fmac_f32_e32 v50, v56, v56
	v_fmac_f32_e32 v50, v58, v58
	v_fmac_f32_e32 v50, v59, v59
	v_add_f32_e32 v88, v88, v50
	s_waitcnt vmcnt(15)
	v_cvt_pk_bf16_f32 v46, v60, v61
	v_cvt_pk_bf16_f32 v47, v62, v63
	global_store_dwordx2 v[86:87], v[46:47], off offset:1024
	v_mul_f32_e32 v50, v61, v61
	v_fmac_f32_e32 v50, v60, v60
	v_fmac_f32_e32 v50, v62, v62
	v_fmac_f32_e32 v50, v63, v63
	v_add_f32_e32 v88, v88, v50
	s_waitcnt vmcnt(15)
; DI u32x2 pk4(f32x4 v) { u32x2 r; r.x = pk2(v[0], v[1]); r.y = pk2(v[2], v[3]); return r; }
; DI void phase0(CP& p, LAS unsigned char* lds, int wid) {
;     ...
;             const int row = it - NCONV; const f32x4* xr = (const f32x4*)(p.x + (size_t)row * 2048); bf16_t* xb = WSB(OFF_XB) + (size_t)row * 2048;
;             float ss = 0.f;
; #pragma unroll
;             for (int i = 0; i < 8; ++i) { const f32x4 v = __builtin_nontemporal_load(xr + i * 64 + lane); ss += v[0] * v[0] + v[1] * v[1] + v[2] * v[2] + v[3] * v[3]; *(u32x2*)(xb + (i * 64 + lane) * 4) = pk4(v); }
; #pragma unroll
;             for (int o = 1; o < 64; o <<= 1) ss += __shfl_xor(ss, o);
;             if (lane == 0) SSQ(0)[row] = ss;
	v_cvt_pk_bf16_f32 v48, v64, v65
	v_cvt_pk_bf16_f32 v49, v66, v67
	global_store_dwordx2 v[86:87], v[48:49], off offset:1536
	v_mul_f32_e32 v50, v65, v65
	v_fmac_f32_e32 v50, v64, v64
	v_fmac_f32_e32 v50, v66, v66
	v_fmac_f32_e32 v50, v67, v67
	v_add_f32_e32 v88, v88, v50
	s_waitcnt vmcnt(15)
	v_cvt_pk_bf16_f32 v46, v68, v69
	v_cvt_pk_bf16_f32 v47, v70, v71
	global_store_dwordx2 v[86:87], v[46:47], off offset:2048
	v_mul_f32_e32 v50, v69, v69
	v_fmac_f32_e32 v50, v68, v68
	v_fmac_f32_e32 v50, v70, v70
	v_fmac_f32_e32 v50, v71, v71
	v_add_f32_e32 v88, v88, v50
	s_waitcnt vmcnt(15)
	v_cvt_pk_bf16_f32 v48, v72, v73
	v_cvt_pk_bf16_f32 v49, v74, v75
	global_store_dwordx2 v[86:87], v[48:49], off offset:2560
	v_mul_f32_e32 v50, v73, v73
	v_fmac_f32_e32 v50, v72, v72
	v_fmac_f32_e32 v50, v74, v74
	v_fmac_f32_e32 v50, v75, v75
	v_add_f32_e32 v88, v88, v50
	s_waitcnt vmcnt(15)
	v_cvt_pk_bf16_f32 v46, v76, v77
	v_cvt_pk_bf16_f32 v47, v78, v79
	global_store_dwordx2 v[86:87], v[46:47], off offset:3072
	v_mul_f32_e32 v50, v77, v77
	v_fmac_f32_e32 v50, v76, v76
	v_fmac_f32_e32 v50, v78, v78
	v_fmac_f32_e32 v50, v79, v79
	v_add_f32_e32 v88, v88, v50
	s_waitcnt vmcnt(15)
	v_cvt_pk_bf16_f32 v48, v80, v81
	v_cvt_pk_bf16_f32 v49, v82, v83
	global_store_dwordx2 v[86:87], v[48:49], off offset:3584
	v_mul_f32_e32 v50, v81, v81
	v_fmac_f32_e32 v50, v80, v80
	v_fmac_f32_e32 v50, v82, v82
	v_fmac_f32_e32 v50, v83, v83
	v_add_f32_e32 v88, v88, v50
	ds_bpermute_b32 v89, v224, v88
	s_waitcnt lgkmcnt(0)
	v_add_f32_e32 v88, v88, v89
	ds_bpermute_b32 v89, v225, v88
	s_waitcnt lgkmcnt(0)
	v_add_f32_e32 v88, v88, v89
	ds_bpermute_b32 v89, v226, v88
	s_waitcnt lgkmcnt(0)
	v_add_f32_e32 v88, v88, v89
	ds_bpermute_b32 v89, v227, v88
	s_waitcnt lgkmcnt(0)
	v_add_f32_e32 v88, v88, v89
	ds_bpermute_b32 v89, v228, v88
	s_waitcnt lgkmcnt(0)
	v_add_f32_e32 v88, v88, v89
	ds_bpermute_b32 v89, v229, v88
	s_waitcnt lgkmcnt(0)
	v_add_f32_e32 v88, v88, v89
	s_and_saveexec_b64 s[74:75], s[2:3]
	s_lshl_b64 s[72:73], s[72:73], 2
	s_add_u32 s72, s91, s72
	s_addc_u32 s73, s92, s73
	global_store_dword v9, v88, s[72:73]
	s_or_b64 exec, exec, s[74:75]
	s_add_i32 s89, s89, s90
	s_branch .Lxr_red
.Lxr_A1:
	s_waitcnt vmcnt(7)
	v_cvt_pk_bf16_f32 v46, v10, v11
	v_cvt_pk_bf16_f32 v47, v12, v13
	global_store_dwordx2 v[42:43], v[46:47], off
	v_mul_f32_e32 v50, v11, v11
	v_fmac_f32_e32 v50, v10, v10
	v_fmac_f32_e32 v50, v12, v12
	v_fmac_f32_e32 v50, v13, v13
	v_mov_b32_e32 v8, v50
	s_waitcnt vmcnt(7)
	v_cvt_pk_bf16_f32 v48, v14, v15
	v_cvt_pk_bf16_f32 v49, v16, v17
	global_store_dwordx2 v[42:43], v[48:49], off offset:512
	v_mul_f32_e32 v50, v15, v15
	v_fmac_f32_e32 v50, v14, v14
	v_fmac_f32_e32 v50, v16, v16
	v_fmac_f32_e32 v50, v17, v17
	v_add_f32_e32 v8, v8, v50
	s_waitcnt vmcnt(7)
	v_cvt_pk_bf16_f32 v46, v18, v19
	v_cvt_pk_bf16_f32 v47, v20, v21
	global_store_dwordx2 v[42:43], v[46:47], off offset:1024
	v_mul_f32_e32 v50, v19, v19
	v_fmac_f32_e32 v50, v18, v18
	v_fmac_f32_e32 v50, v20, v20
	v_fmac_f32_e32 v50, v21, v21
	v_add_f32_e32 v8, v8, v50
	s_waitcnt vmcnt(7)
	v_cvt_pk_bf16_f32 v48, v22, v23
	v_cvt_pk_bf16_f32 v49, v24, v25
	global_store_dwordx2 v[42:43], v[48:49], off offset:1536
	v_mul_f32_e32 v50, v23, v23
	v_fmac_f32_e32 v50, v22, v22
	v_fmac_f32_e32 v50, v24, v24
	v_fmac_f32_e32 v50, v25, v25
	v_add_f32_e32 v8, v8, v50
	s_waitcnt vmcnt(7)
	v_cvt_pk_bf16_f32 v46, v26, v27
	v_cvt_pk_bf16_f32 v47, v28, v29
	global_store_dwordx2 v[42:43], v[46:47], off offset:2048
	v_mul_f32_e32 v50, v27, v27
	v_fmac_f32_e32 v50, v26, v26
	v_fmac_f32_e32 v50, v28, v28
	v_fmac_f32_e32 v50, v29, v29
	v_add_f32_e32 v8, v8, v50
	s_waitcnt vmcnt(7)
	v_cvt_pk_bf16_f32 v48, v30, v31
	v_cvt_pk_bf16_f32 v49, v32, v33
	global_store_dwordx2 v[42:43], v[48:49], off offset:2560
	v_mul_f32_e32 v50, v31, v31
	v_fmac_f32_e32 v50, v30, v30
	v_fmac_f32_e32 v50, v32, v32
	v_fmac_f32_e32 v50, v33, v33
	v_add_f32_e32 v8, v8, v50
	s_waitcnt vmcnt(7)
	v_cvt_pk_bf16_f32 v46, v34, v35
	v_cvt_pk_bf16_f32 v47, v36, v37
	global_store_dwordx2 v[42:43], v[46:47], off offset:3072
	v_mul_f32_e32 v50, v35, v35
	v_fmac_f32_e32 v50, v34, v34
	v_fmac_f32_e32 v50, v36, v36
	v_fmac_f32_e32 v50, v37, v37
	v_add_f32_e32 v8, v8, v50
	s_waitcnt vmcnt(7)
	v_cvt_pk_bf16_f32 v48, v38, v39
	v_cvt_pk_bf16_f32 v49, v40, v41
	global_store_dwordx2 v[42:43], v[48:49], off offset:3584
	v_mul_f32_e32 v50, v39, v39
	v_fmac_f32_e32 v50, v38, v38
	v_fmac_f32_e32 v50, v40, v40
	v_fmac_f32_e32 v50, v41, v41
	v_add_f32_e32 v8, v8, v50
.Lxr_red:
	ds_bpermute_b32 v10, v224, v8
	s_waitcnt lgkmcnt(0)
	v_add_f32_e32 v8, v8, v10
	ds_bpermute_b32 v10, v225, v8
	s_waitcnt lgkmcnt(0)
	v_add_f32_e32 v8, v8, v10
	ds_bpermute_b32 v10, v226, v8
	s_waitcnt lgkmcnt(0)
	v_add_f32_e32 v8, v8, v10
	ds_bpermute_b32 v10, v227, v8
	s_waitcnt lgkmcnt(0)
	v_add_f32_e32 v8, v8, v10
	ds_bpermute_b32 v10, v228, v8
	s_waitcnt lgkmcnt(0)
	v_add_f32_e32 v8, v8, v10
	ds_bpermute_b32 v10, v229, v8
	s_and_saveexec_b64 s[70:71], s[2:3]
	s_cbranch_execz .LBB0_26
	s_lshl_b64 s[42:43], s[40:41], 2
	s_add_u32 s42, s91, s42
	s_addc_u32 s43, s92, s43
	s_waitcnt lgkmcnt(0)
	v_add_f32_e32 v8, v8, v10
	global_store_dword v9, v8, s[42:43]

; DI float bf_lo(unsigned w) { return __uint_as_float(w << 16); }
; DI float bf_hi(unsigned w) { return __uint_as_float(w & 0xffff0000u); }
; DI float rstd_of(float ssq, float inv_n) { return __builtin_amdgcn_rsqf(ssq * inv_n + 1e-6f); }
; DI int lane_id() { int l = __builtin_amdgcn_mbcnt_hi(-1, __builtin_amdgcn_mbcnt_lo(-1, 0)); asm volatile("" : "+v"(l)); return l; }
; DI void phase_final(CP& p, int wid) {
;     const int lane = lane_id();
;     for (int it = blockIdx.x; it < 1024; it += gridDim.x) {
;         const int row = it * 8 + wid; const float rs = rstd_of(SSQ(7)[row], 1.f / 2048.f);
;         const u32x4* xr = (const u32x4*)(WSB(OFF_XB) + (size_t)row * 2048); f32x4* orow = (f32x4*)(p.out + (size_t)row * 2048); const f32x4* gf = (const f32x4*)p.g_final;
; #pragma unroll
;         for (int i = 0; i < 4; ++i) { const u32x4 w = xr[i * 64 + lane]; const int c = (i * 64 + lane) * 2;
;             const f32x4 a = {bf_lo(w.x), bf_hi(w.x), bf_lo(w.y), bf_hi(w.y)}, b = {bf_lo(w.z), bf_hi(w.z), bf_lo(w.w), bf_hi(w.w)};
;             orow[c] = a * rs * gf[c]; orow[c + 1] = b * rs * gf[c + 1]; }
;     }
; }
.LBB0_1419:
	s_ashr_i32 s1, s0, 31
	s_lshl_b64 s[2:3], s[0:1], 2
	s_add_u32 s2, s4, s2
	s_addc_u32 s3, s5, s3
	global_load_dword v32, v18, s[2:3]
	s_lshl_b64 s[14:15], s[0:1], 13
	s_add_u32 s14, s8, s14
	s_addc_u32 s15, s9, s15
	s_lshl_b64 s[12:13], s[0:1], 12
	v_lshl_add_u64 v[28:29], v[16:17], 0, s[12:13]
	global_load_dwordx4 v[72:75], v[28:29], off
	global_load_dwordx4 v[76:79], v[28:29], off offset:1024
	global_load_dwordx4 v[80:83], v[28:29], off offset:2048
	global_load_dwordx4 v[84:87], v[28:29], off offset:3072
	s_add_i32 s6, s6, s7
	s_cmpk_lt_i32 s6, 0x400
	s_cbranch_scc0 .Lp13_one
	s_add_i32 s16, s0, s10
	s_ashr_i32 s17, s16, 31
	s_lshl_b64 s[2:3], s[16:17], 2
	s_add_u32 s2, s4, s2
	s_addc_u32 s3, s5, s3
	global_load_dword v92, v18, s[2:3]
	s_lshl_b64 s[18:19], s[16:17], 13
	s_add_u32 s18, s8, s18
	s_addc_u32 s19, s9, s19
	s_lshl_b64 s[12:13], s[16:17], 12
	v_lshl_add_u64 v[38:39], v[16:17], 0, s[12:13]
	global_load_dwordx4 v[96:99], v[38:39], off
	global_load_dwordx4 v[100:103], v[38:39], off offset:1024
	global_load_dwordx4 v[104:107], v[38:39], off offset:2048
	global_load_dwordx4 v[108:111], v[38:39], off offset:3072
	s_waitcnt vmcnt(9)
	v_fmamk_f32 v32, v32, 0x3a000000, v19
	v_rsq_f32_e32 v32, v32
	v_lshl_add_u64 v[30:31], v[0:1], 4, s[14:15]
	s_waitcnt vmcnt(8)
	v_lshlrev_b32_e32 v34, 16, v72
	v_and_b32_e32 v35, 0xffff0000, v72
	v_lshlrev_b32_e32 v36, 16, v73
	v_and_b32_e32 v37, 0xffff0000, v73
	v_pk_mul_f32 v[34:35], v[32:33], v[34:35] op_sel_hi:[0,1]
	v_pk_mul_f32 v[36:37], v[32:33], v[36:37] op_sel_hi:[0,1]
	v_pk_mul_f32 v[112:113], v[40:41], v[34:35]
	v_pk_mul_f32 v[114:115], v[42:43], v[36:37]
	global_store_dwordx4 v[30:31], v[112:115], off
	v_lshlrev_b32_e32 v34, 16, v74
	v_and_b32_e32 v35, 0xffff0000, v74
	v_lshlrev_b32_e32 v36, 16, v75
	v_and_b32_e32 v37, 0xffff0000, v75
	v_pk_mul_f32 v[34:35], v[32:33], v[34:35] op_sel_hi:[0,1]
	v_pk_mul_f32 v[36:37], v[32:33], v[36:37] op_sel_hi:[0,1]
	v_pk_mul_f32 v[116:117], v[44:45], v[34:35]
	v_pk_mul_f32 v[118:119], v[46:47], v[36:37]
	global_store_dwordx4 v[30:31], v[116:119], off offset:16
	v_lshl_add_u64 v[30:31], v[4:5], 4, s[14:15]
	s_waitcnt vmcnt(9)
	v_lshlrev_b32_e32 v34, 16, v76
	v_and_b32_e32 v35, 0xffff0000, v76
	v_lshlrev_b32_e32 v36, 16, v77
	v_and_b32_e32 v37, 0xffff0000, v77
	v_pk_mul_f32 v[34:35], v[32:33], v[34:35] op_sel_hi:[0,1]
	v_pk_mul_f32 v[36:37], v[32:33], v[36:37] op_sel_hi:[0,1]
	v_pk_mul_f32 v[112:113], v[48:49], v[34:35]
	v_pk_mul_f32 v[114:115], v[50:51], v[36:37]
	global_store_dwordx4 v[30:31], v[112:115], off
	v_lshlrev_b32_e32 v34, 16, v78
	v_and_b32_e32 v35, 0xffff0000, v78
	v_lshlrev_b32_e32 v36, 16, v79
	v_and_b32_e32 v37, 0xffff0000, v79
	v_pk_mul_f32 v[34:35], v[32:33], v[34:35] op_sel_hi:[0,1]
	v_pk_mul_f32 v[36:37], v[32:33], v[36:37] op_sel_hi:[0,1]
	v_pk_mul_f32 v[116:117], v[52:53], v[34:35]
	v_pk_mul_f32 v[118:119], v[54:55], v[36:37]
	global_store_dwordx4 v[30:31], v[116:119], off offset:16
	v_lshl_add_u64 v[30:31], v[8:9], 4, s[14:15]
	s_waitcnt vmcnt(10)
	v_lshlrev_b32_e32 v34, 16, v80
	v_and_b32_e32 v35, 0xffff0000, v80
	v_lshlrev_b32_e32 v36, 16, v81
	v_and_b32_e32 v37, 0xffff0000, v81
	v_pk_mul_f32 v[34:35], v[32:33], v[34:35] op_sel_hi:[0,1]
	v_pk_mul_f32 v[36:37], v[32:33], v[36:37] op_sel_hi:[0,1]
	v_pk_mul_f32 v[112:113], v[56:57], v[34:35]
	v_pk_mul_f32 v[114:115], v[58:59], v[36:37]
	global_store_dwordx4 v[30:31], v[112:115], off
	v_lshlrev_b32_e32 v34, 16, v82
	v_and_b32_e32 v35, 0xffff0000, v82
	v_lshlrev_b32_e32 v36, 16, v83
	v_and_b32_e32 v37, 0xffff0000, v83
	v_pk_mul_f32 v[34:35], v[32:33], v[34:35] op_sel_hi:[0,1]
	v_pk_mul_f32 v[36:37], v[32:33], v[36:37] op_sel_hi:[0,1]
	v_pk_mul_f32 v[116:117], v[60:61], v[34:35]
	v_pk_mul_f32 v[118:119], v[62:63], v[36:37]
	global_store_dwordx4 v[30:31], v[116:119], off offset:16
	v_lshl_add_u64 v[30:31], v[12:13], 4, s[14:15]
	s_waitcnt vmcnt(11)
	v_lshlrev_b32_e32 v34, 16, v84
	v_and_b32_e32 v35, 0xffff0000, v84
	v_lshlrev_b32_e32 v36, 16, v85
	v_and_b32_e32 v37, 0xffff0000, v85
	v_pk_mul_f32 v[34:35], v[32:33], v[34:35] op_sel_hi:[0,1]
	v_pk_mul_f32 v[36:37], v[32:33], v[36:37] op_sel_hi:[0,1]
	v_pk_mul_f32 v[112:113], v[64:65], v[34:35]
	v_pk_mul_f32 v[114:115], v[66:67], v[36:37]
	global_store_dwordx4 v[30:31], v[112:115], off
	v_lshlrev_b32_e32 v34, 16, v86
	v_and_b32_e32 v35, 0xffff0000, v86
	v_lshlrev_b32_e32 v36, 16, v87
	v_and_b32_e32 v37, 0xffff0000, v87
	v_pk_mul_f32 v[34:35], v[32:33], v[34:35] op_sel_hi:[0,1]
	v_pk_mul_f32 v[36:37], v[32:33], v[36:37] op_sel_hi:[0,1]
	v_pk_mul_f32 v[116:117], v[68:69], v[34:35]
	v_pk_mul_f32 v[118:119], v[70:71], v[36:37]
	global_store_dwordx4 v[30:31], v[116:119], off offset:16
	s_waitcnt vmcnt(12)
	v_fmamk_f32 v92, v92, 0x3a000000, v19
	v_rsq_f32_e32 v92, v92
	v_lshl_add_u64 v[30:31], v[0:1], 4, s[18:19]
	s_waitcnt vmcnt(11)
	v_lshlrev_b32_e32 v34, 16, v96
	v_and_b32_e32 v35, 0xffff0000, v96
	v_lshlrev_b32_e32 v36, 16, v97
	v_and_b32_e32 v37, 0xffff0000, v97
	v_pk_mul_f32 v[34:35], v[92:93], v[34:35] op_sel_hi:[0,1]
	v_pk_mul_f32 v[36:37], v[92:93], v[36:37] op_sel_hi:[0,1]
	v_pk_mul_f32 v[112:113], v[40:41], v[34:35]
	v_pk_mul_f32 v[114:115], v[42:43], v[36:37]
	global_store_dwordx4 v[30:31], v[112:115], off
	v_lshlrev_b32_e32 v34, 16, v98
	v_and_b32_e32 v35, 0xffff0000, v98
	v_lshlrev_b32_e32 v36, 16, v99
	v_and_b32_e32 v37, 0xffff0000, v99
	v_pk_mul_f32 v[34:35], v[92:93], v[34:35] op_sel_hi:[0,1]
	v_pk_mul_f32 v[36:37], v[92:93], v[36:37] op_sel_hi:[0,1]
	v_pk_mul_f32 v[116:117], v[44:45], v[34:35]
	v_pk_mul_f32 v[118:119], v[46:47], v[36:37]
	global_store_dwordx4 v[30:31], v[116:119], off offset:16
	v_lshl_add_u64 v[30:31], v[4:5], 4, s[18:19]
	s_waitcnt vmcnt(12)
; DI float bf_lo(unsigned w) { return __uint_as_float(w << 16); }
; DI float bf_hi(unsigned w) { return __uint_as_float(w & 0xffff0000u); }
; DI float rstd_of(float ssq, float inv_n) { return __builtin_amdgcn_rsqf(ssq * inv_n + 1e-6f); }
; DI int lane_id() { int l = __builtin_amdgcn_mbcnt_hi(-1, __builtin_amdgcn_mbcnt_lo(-1, 0)); asm volatile("" : "+v"(l)); return l; }
; DI void phase_final(CP& p, int wid) {
;     const int lane = lane_id();
;     for (int it = blockIdx.x; it < 1024; it += gridDim.x) {
;         const int row = it * 8 + wid; const float rs = rstd_of(SSQ(7)[row], 1.f / 2048.f);
;         const u32x4* xr = (const u32x4*)(WSB(OFF_XB) + (size_t)row * 2048); f32x4* orow = (f32x4*)(p.out + (size_t)row * 2048); const f32x4* gf = (const f32x4*)p.g_final;
; #pragma unroll
;         for (int i = 0; i < 4; ++i) { const u32x4 w = xr[i * 64 + lane]; const int c = (i * 64 + lane) * 2;
;             const f32x4 a = {bf_lo(w.x), bf_hi(w.x), bf_lo(w.y), bf_hi(w.y)}, b = {bf_lo(w.z), bf_hi(w.z), bf_lo(w.w), bf_hi(w.w)};
;             orow[c] = a * rs * gf[c]; orow[c + 1] = b * rs * gf[c + 1]; }
;     }
; }
	v_lshlrev_b32_e32 v34, 16, v100
	v_and_b32_e32 v35, 0xffff0000, v100
	v_lshlrev_b32_e32 v36, 16, v101
	v_and_b32_e32 v37, 0xffff0000, v101
	v_pk_mul_f32 v[34:35], v[92:93], v[34:35] op_sel_hi:[0,1]
	v_pk_mul_f32 v[36:37], v[92:93], v[36:37] op_sel_hi:[0,1]
	v_pk_mul_f32 v[112:113], v[48:49], v[34:35]
	v_pk_mul_f32 v[114:115], v[50:51], v[36:37]
	global_store_dwordx4 v[30:31], v[112:115], off
	v_lshlrev_b32_e32 v34, 16, v102
	v_and_b32_e32 v35, 0xffff0000, v102
	v_lshlrev_b32_e32 v36, 16, v103
	v_and_b32_e32 v37, 0xffff0000, v103
	v_pk_mul_f32 v[34:35], v[92:93], v[34:35] op_sel_hi:[0,1]
	v_pk_mul_f32 v[36:37], v[92:93], v[36:37] op_sel_hi:[0,1]
	v_pk_mul_f32 v[116:117], v[52:53], v[34:35]
	v_pk_mul_f32 v[118:119], v[54:55], v[36:37]
	global_store_dwordx4 v[30:31], v[116:119], off offset:16
	v_lshl_add_u64 v[30:31], v[8:9], 4, s[18:19]
	s_waitcnt vmcnt(13)
	v_lshlrev_b32_e32 v34, 16, v104
	v_and_b32_e32 v35, 0xffff0000, v104
	v_lshlrev_b32_e32 v36, 16, v105
	v_and_b32_e32 v37, 0xffff0000, v105
	v_pk_mul_f32 v[34:35], v[92:93], v[34:35] op_sel_hi:[0,1]
	v_pk_mul_f32 v[36:37], v[92:93], v[36:37] op_sel_hi:[0,1]
	v_pk_mul_f32 v[112:113], v[56:57], v[34:35]
	v_pk_mul_f32 v[114:115], v[58:59], v[36:37]
	global_store_dwordx4 v[30:31], v[112:115], off
	v_lshlrev_b32_e32 v34, 16, v106
	v_and_b32_e32 v35, 0xffff0000, v106
	v_lshlrev_b32_e32 v36, 16, v107
	v_and_b32_e32 v37, 0xffff0000, v107
	v_pk_mul_f32 v[34:35], v[92:93], v[34:35] op_sel_hi:[0,1]
	v_pk_mul_f32 v[36:37], v[92:93], v[36:37] op_sel_hi:[0,1]
	v_pk_mul_f32 v[116:117], v[60:61], v[34:35]
	v_pk_mul_f32 v[118:119], v[62:63], v[36:37]
	global_store_dwordx4 v[30:31], v[116:119], off offset:16
	v_lshl_add_u64 v[30:31], v[12:13], 4, s[18:19]
	s_waitcnt vmcnt(14)
	v_lshlrev_b32_e32 v34, 16, v108
	v_and_b32_e32 v35, 0xffff0000, v108
	v_lshlrev_b32_e32 v36, 16, v109
	v_and_b32_e32 v37, 0xffff0000, v109
	v_pk_mul_f32 v[34:35], v[92:93], v[34:35] op_sel_hi:[0,1]
	v_pk_mul_f32 v[36:37], v[92:93], v[36:37] op_sel_hi:[0,1]
	v_pk_mul_f32 v[112:113], v[64:65], v[34:35]
	v_pk_mul_f32 v[114:115], v[66:67], v[36:37]
	global_store_dwordx4 v[30:31], v[112:115], off
	v_lshlrev_b32_e32 v34, 16, v110
	v_and_b32_e32 v35, 0xffff0000, v110
	v_lshlrev_b32_e32 v36, 16, v111
	v_and_b32_e32 v37, 0xffff0000, v111
	v_pk_mul_f32 v[34:35], v[92:93], v[34:35] op_sel_hi:[0,1]
	v_pk_mul_f32 v[36:37], v[92:93], v[36:37] op_sel_hi:[0,1]
	v_pk_mul_f32 v[116:117], v[68:69], v[34:35]
	v_pk_mul_f32 v[118:119], v[70:71], v[36:37]
	global_store_dwordx4 v[30:31], v[116:119], off offset:16
	s_add_i32 s6, s6, s7
	s_add_i32 s0, s0, s10
	s_branch .Lp13_next
.Lp13_one:
	s_waitcnt vmcnt(4)
	v_fmamk_f32 v32, v32, 0x3a000000, v19
	v_rsq_f32_e32 v32, v32
	v_lshl_add_u64 v[30:31], v[0:1], 4, s[14:15]
	s_waitcnt vmcnt(3)
	v_lshlrev_b32_e32 v34, 16, v72
	v_and_b32_e32 v35, 0xffff0000, v72
	v_lshlrev_b32_e32 v36, 16, v73
	v_and_b32_e32 v37, 0xffff0000, v73
	v_pk_mul_f32 v[34:35], v[32:33], v[34:35] op_sel_hi:[0,1]
	v_pk_mul_f32 v[36:37], v[32:33], v[36:37] op_sel_hi:[0,1]
	v_pk_mul_f32 v[112:113], v[40:41], v[34:35]
	v_pk_mul_f32 v[114:115], v[42:43], v[36:37]
	global_store_dwordx4 v[30:31], v[112:115], off
	v_lshlrev_b32_e32 v34, 16, v74
	v_and_b32_e32 v35, 0xffff0000, v74
	v_lshlrev_b32_e32 v36, 16, v75
	v_and_b32_e32 v37, 0xffff0000, v75
	v_pk_mul_f32 v[34:35], v[32:33], v[34:35] op_sel_hi:[0,1]
	v_pk_mul_f32 v[36:37], v[32:33], v[36:37] op_sel_hi:[0,1]
	v_pk_mul_f32 v[116:117], v[44:45], v[34:35]
	v_pk_mul_f32 v[118:119], v[46:47], v[36:37]
	global_store_dwordx4 v[30:31], v[116:119], off offset:16
	v_lshl_add_u64 v[30:31], v[4:5], 4, s[14:15]
	s_waitcnt vmcnt(4)
	v_lshlrev_b32_e32 v34, 16, v76
	v_and_b32_e32 v35, 0xffff0000, v76
	v_lshlrev_b32_e32 v36, 16, v77
	v_and_b32_e32 v37, 0xffff0000, v77
	v_pk_mul_f32 v[34:35], v[32:33], v[34:35] op_sel_hi:[0,1]
	v_pk_mul_f32 v[36:37], v[32:33], v[36:37] op_sel_hi:[0,1]
	v_pk_mul_f32 v[112:113], v[48:49], v[34:35]
	v_pk_mul_f32 v[114:115], v[50:51], v[36:37]
	global_store_dwordx4 v[30:31], v[112:115], off
	v_lshlrev_b32_e32 v34, 16, v78
	v_and_b32_e32 v35, 0xffff0000, v78
	v_lshlrev_b32_e32 v36, 16, v79
	v_and_b32_e32 v37, 0xffff0000, v79
	v_pk_mul_f32 v[34:35], v[32:33], v[34:35] op_sel_hi:[0,1]
	v_pk_mul_f32 v[36:37], v[32:33], v[36:37] op_sel_hi:[0,1]
	v_pk_mul_f32 v[116:117], v[52:53], v[34:35]
	v_pk_mul_f32 v[118:119], v[54:55], v[36:37]
	global_store_dwordx4 v[30:31], v[116:119], off offset:16
	v_lshl_add_u64 v[30:31], v[8:9], 4, s[14:15]
	s_waitcnt vmcnt(5)
	v_lshlrev_b32_e32 v34, 16, v80
	v_and_b32_e32 v35, 0xffff0000, v80
	v_lshlrev_b32_e32 v36, 16, v81
	v_and_b32_e32 v37, 0xffff0000, v81
	v_pk_mul_f32 v[34:35], v[32:33], v[34:35] op_sel_hi:[0,1]
	v_pk_mul_f32 v[36:37], v[32:33], v[36:37] op_sel_hi:[0,1]
	v_pk_mul_f32 v[112:113], v[56:57], v[34:35]
	v_pk_mul_f32 v[114:115], v[58:59], v[36:37]
	global_store_dwordx4 v[30:31], v[112:115], off
	v_lshlrev_b32_e32 v34, 16, v82
	v_and_b32_e32 v35, 0xffff0000, v82
	v_lshlrev_b32_e32 v36, 16, v83
	v_and_b32_e32 v37, 0xffff0000, v83
	v_pk_mul_f32 v[34:35], v[32:33], v[34:35] op_sel_hi:[0,1]
	v_pk_mul_f32 v[36:37], v[32:33], v[36:37] op_sel_hi:[0,1]
	v_pk_mul_f32 v[116:117], v[60:61], v[34:35]
	v_pk_mul_f32 v[118:119], v[62:63], v[36:37]
	global_store_dwordx4 v[30:31], v[116:119], off offset:16
	v_lshl_add_u64 v[30:31], v[12:13], 4, s[14:15]
	s_waitcnt vmcnt(6)
	v_lshlrev_b32_e32 v34, 16, v84
	v_and_b32_e32 v35, 0xffff0000, v84
	v_lshlrev_b32_e32 v36, 16, v85
	v_and_b32_e32 v37, 0xffff0000, v85
	v_pk_mul_f32 v[34:35], v[32:33], v[34:35] op_sel_hi:[0,1]
	v_pk_mul_f32 v[36:37], v[32:33], v[36:37] op_sel_hi:[0,1]
	v_pk_mul_f32 v[112:113], v[64:65], v[34:35]
	v_pk_mul_f32 v[114:115], v[66:67], v[36:37]
	global_store_dwordx4 v[30:31], v[112:115], off
	v_lshlrev_b32_e32 v34, 16, v86
	v_and_b32_e32 v35, 0xffff0000, v86
	v_lshlrev_b32_e32 v36, 16, v87
	v_and_b32_e32 v37, 0xffff0000, v87
	v_pk_mul_f32 v[34:35], v[32:33], v[34:35] op_sel_hi:[0,1]
	v_pk_mul_f32 v[36:37], v[32:33], v[36:37] op_sel_hi:[0,1]
	v_pk_mul_f32 v[116:117], v[68:69], v[34:35]
	v_pk_mul_f32 v[118:119], v[70:71], v[36:37]
	global_store_dwordx4 v[30:31], v[116:119], off offset:16
.Lp13_next:
	s_add_i32 s0, s0, s10
	s_cmpk_lt_i32 s6, 0x400
	s_cbranch_scc1 .LBB0_1419
